# merge output stores and chunk-record stores marked nt
# baseline (speedup 1.0000x reference)
.Lfm_wdone:
	v_max3_f32 v127, v24, v25, v26
	v_sub_f32_e32 v102, v24, v127
	v_sub_f32_e32 v104, v25, v127
	v_sub_f32_e32 v106, v26, v127
	v_mul_f32_e32 v102, 0x3fb8aa3b, v102
	v_mul_f32_e32 v104, 0x3fb8aa3b, v104
	v_mul_f32_e32 v106, 0x3fb8aa3b, v106
	v_exp_f32_e32 v102, v102
	v_exp_f32_e32 v104, v104
	v_exp_f32_e32 v106, v106
	s_nop 0
	v_add_f32_e32 v127, v102, v104
	v_add_f32_e32 v127, v106, v127
	v_div_scale_f32 v122, s[72:73], v127, v127, 1.0
	v_rcp_f32_e32 v123, v122
	v_div_scale_f32 v124, vcc, 1.0, v127, 1.0
	v_fma_f32 v126, -v122, v123, 1.0
	v_fmac_f32_e32 v123, v126, v123
	v_mul_f32_e32 v125, v124, v123
	v_fma_f32 v126, -v122, v125, v124
	v_fmac_f32_e32 v125, v126, v123
	v_fma_f32 v122, -v122, v125, v124
	v_div_fmas_f32 v122, v122, v123, v125
	v_div_fixup_f32 v103, v122, v127, 1.0
	v_mul_f32_e32 v102, v102, v103
	v_mul_f32_e32 v104, v104, v103
	v_mul_f32_e32 v106, v106, v103
	v_lshlrev_b32_e32 v108, 16, v28
	v_and_b32_e32 v109, 0xffff0000, v28
	v_lshlrev_b32_e32 v110, 16, v32
	v_and_b32_e32 v111, 0xffff0000, v32
	v_lshlrev_b32_e32 v112, 16, v36
	v_and_b32_e32 v113, 0xffff0000, v36
	v_lshlrev_b32_e32 v114, 16, v44
	v_and_b32_e32 v115, 0xffff0000, v44
	v_pk_mul_f32 v[116:117], v[108:109], v[102:103] op_sel_hi:[1,0]
	v_pk_fma_f32 v[116:117], v[110:111], v[104:105], v[116:117] op_sel_hi:[1,0,1]
	v_pk_fma_f32 v[116:117], v[112:113], v[106:107], v[116:117] op_sel_hi:[1,0,1]
	v_pk_mul_f32 v[118:119], v[114:115], s[44:45]
	v_exp_f32_e32 v118, v118
	v_exp_f32_e32 v119, v119
	s_nop 0
	v_pk_add_f32 v[118:119], v[118:119], 1.0 op_sel_hi:[1,0]
	v_div_scale_f32 v122, s[72:73], v118, v118, v114
	v_rcp_f32_e32 v123, v122
	v_div_scale_f32 v124, vcc, v114, v118, v114
	v_fma_f32 v126, -v122, v123, 1.0
	v_fmac_f32_e32 v123, v126, v123
	v_mul_f32_e32 v125, v124, v123
	v_fma_f32 v126, -v122, v125, v124
	v_fmac_f32_e32 v125, v126, v123
	v_fma_f32 v122, -v122, v125, v124
	v_div_fmas_f32 v122, v122, v123, v125
	v_div_fixup_f32 v120, v122, v118, v114
	v_div_scale_f32 v122, s[72:73], v119, v119, v115
	v_rcp_f32_e32 v123, v122
	v_div_scale_f32 v124, vcc, v115, v119, v115
	v_fma_f32 v126, -v122, v123, 1.0
	v_fmac_f32_e32 v123, v126, v123
	v_mul_f32_e32 v125, v124, v123
	v_fma_f32 v126, -v122, v125, v124
	v_fmac_f32_e32 v125, v126, v123
	v_fma_f32 v122, -v122, v125, v124
	v_div_fmas_f32 v122, v122, v123, v125
	v_div_fixup_f32 v121, v122, v119, v115
	v_pk_mul_f32 v[116:117], v[120:121], v[116:117]
	v_cvt_pk_bf16_f32 v128, v116, v117
	v_lshlrev_b32_e32 v108, 16, v29
	v_and_b32_e32 v109, 0xffff0000, v29
	v_lshlrev_b32_e32 v110, 16, v33
	v_and_b32_e32 v111, 0xffff0000, v33
	v_lshlrev_b32_e32 v112, 16, v37
	v_and_b32_e32 v113, 0xffff0000, v37
	v_lshlrev_b32_e32 v114, 16, v45
	v_and_b32_e32 v115, 0xffff0000, v45
	v_pk_mul_f32 v[116:117], v[108:109], v[102:103] op_sel_hi:[1,0]
	v_pk_fma_f32 v[116:117], v[110:111], v[104:105], v[116:117] op_sel_hi:[1,0,1]
	v_pk_fma_f32 v[116:117], v[112:113], v[106:107], v[116:117] op_sel_hi:[1,0,1]
	v_pk_mul_f32 v[118:119], v[114:115], s[44:45]
	v_exp_f32_e32 v118, v118
	v_exp_f32_e32 v119, v119
	s_nop 0
	v_pk_add_f32 v[118:119], v[118:119], 1.0 op_sel_hi:[1,0]
	v_div_scale_f32 v122, s[72:73], v118, v118, v114
	v_rcp_f32_e32 v123, v122
	v_div_scale_f32 v124, vcc, v114, v118, v114
	v_fma_f32 v126, -v122, v123, 1.0
	v_fmac_f32_e32 v123, v126, v123
	v_mul_f32_e32 v125, v124, v123
	v_fma_f32 v126, -v122, v125, v124
	v_fmac_f32_e32 v125, v126, v123
	v_fma_f32 v122, -v122, v125, v124
	v_div_fmas_f32 v122, v122, v123, v125
	v_div_fixup_f32 v120, v122, v118, v114
	v_div_scale_f32 v122, s[72:73], v119, v119, v115
	v_rcp_f32_e32 v123, v122
	v_div_scale_f32 v124, vcc, v115, v119, v115
	v_fma_f32 v126, -v122, v123, 1.0
	v_fmac_f32_e32 v123, v126, v123
	v_mul_f32_e32 v125, v124, v123
	v_fma_f32 v126, -v122, v125, v124
	v_fmac_f32_e32 v125, v126, v123
	v_fma_f32 v122, -v122, v125, v124
	v_div_fmas_f32 v122, v122, v123, v125
	v_div_fixup_f32 v121, v122, v119, v115
	v_pk_mul_f32 v[116:117], v[120:121], v[116:117]
	v_cvt_pk_bf16_f32 v129, v116, v117
	v_lshlrev_b32_e32 v108, 16, v30
	v_and_b32_e32 v109, 0xffff0000, v30
	v_lshlrev_b32_e32 v110, 16, v34
	v_and_b32_e32 v111, 0xffff0000, v34
	v_lshlrev_b32_e32 v112, 16, v38
	v_and_b32_e32 v113, 0xffff0000, v38
	v_lshlrev_b32_e32 v114, 16, v46
	v_and_b32_e32 v115, 0xffff0000, v46
	v_pk_mul_f32 v[116:117], v[108:109], v[102:103] op_sel_hi:[1,0]
	v_pk_fma_f32 v[116:117], v[110:111], v[104:105], v[116:117] op_sel_hi:[1,0,1]
	v_pk_fma_f32 v[116:117], v[112:113], v[106:107], v[116:117] op_sel_hi:[1,0,1]
	v_pk_mul_f32 v[118:119], v[114:115], s[44:45]
	v_exp_f32_e32 v118, v118
	v_exp_f32_e32 v119, v119
	s_nop 0
	v_pk_add_f32 v[118:119], v[118:119], 1.0 op_sel_hi:[1,0]
	v_div_scale_f32 v122, s[72:73], v118, v118, v114
	v_rcp_f32_e32 v123, v122
	v_div_scale_f32 v124, vcc, v114, v118, v114
	v_fma_f32 v126, -v122, v123, 1.0
	v_fmac_f32_e32 v123, v126, v123
	v_mul_f32_e32 v125, v124, v123
	v_fma_f32 v126, -v122, v125, v124
	v_fmac_f32_e32 v125, v126, v123
	v_fma_f32 v122, -v122, v125, v124
	v_div_fmas_f32 v122, v122, v123, v125
	v_div_fixup_f32 v120, v122, v118, v114
	v_div_scale_f32 v122, s[72:73], v119, v119, v115
	v_rcp_f32_e32 v123, v122
	v_div_scale_f32 v124, vcc, v115, v119, v115
	v_fma_f32 v126, -v122, v123, 1.0
	v_fmac_f32_e32 v123, v126, v123
	v_mul_f32_e32 v125, v124, v123
	v_fma_f32 v126, -v122, v125, v124
	v_fmac_f32_e32 v125, v126, v123
	v_fma_f32 v122, -v122, v125, v124
	v_div_fmas_f32 v122, v122, v123, v125
	v_div_fixup_f32 v121, v122, v119, v115
	v_pk_mul_f32 v[116:117], v[120:121], v[116:117]
	v_cvt_pk_bf16_f32 v130, v116, v117
	v_lshlrev_b32_e32 v108, 16, v31
	v_and_b32_e32 v109, 0xffff0000, v31
	v_lshlrev_b32_e32 v110, 16, v35
	v_and_b32_e32 v111, 0xffff0000, v35
	v_lshlrev_b32_e32 v112, 16, v39
	v_and_b32_e32 v113, 0xffff0000, v39
	v_lshlrev_b32_e32 v114, 16, v47
	v_and_b32_e32 v115, 0xffff0000, v47
	v_pk_mul_f32 v[116:117], v[108:109], v[102:103] op_sel_hi:[1,0]
	v_pk_fma_f32 v[116:117], v[110:111], v[104:105], v[116:117] op_sel_hi:[1,0,1]
	v_pk_fma_f32 v[116:117], v[112:113], v[106:107], v[116:117] op_sel_hi:[1,0,1]
	v_pk_mul_f32 v[118:119], v[114:115], s[44:45]
	v_exp_f32_e32 v118, v118
	v_exp_f32_e32 v119, v119
	s_nop 0
	v_pk_add_f32 v[118:119], v[118:119], 1.0 op_sel_hi:[1,0]
	v_div_scale_f32 v122, s[72:73], v118, v118, v114
	v_rcp_f32_e32 v123, v122
	v_div_scale_f32 v124, vcc, v114, v118, v114
	v_fma_f32 v126, -v122, v123, 1.0
	v_fmac_f32_e32 v123, v126, v123
	v_mul_f32_e32 v125, v124, v123
	v_fma_f32 v126, -v122, v125, v124
	v_fmac_f32_e32 v125, v126, v123
	v_fma_f32 v122, -v122, v125, v124
	v_div_fmas_f32 v122, v122, v123, v125
	v_div_fixup_f32 v120, v122, v118, v114
	v_div_scale_f32 v122, s[72:73], v119, v119, v115
	v_rcp_f32_e32 v123, v122
	v_div_scale_f32 v124, vcc, v115, v119, v115
	v_fma_f32 v126, -v122, v123, 1.0
	v_fmac_f32_e32 v123, v126, v123
	v_mul_f32_e32 v125, v124, v123
	v_fma_f32 v126, -v122, v125, v124
	v_fmac_f32_e32 v125, v126, v123
	v_fma_f32 v122, -v122, v125, v124
	v_div_fmas_f32 v122, v122, v123, v125
	v_div_fixup_f32 v121, v122, v119, v115
	v_pk_mul_f32 v[116:117], v[120:121], v[116:117]
	v_cvt_pk_bf16_f32 v131, v116, v117
	global_store_dwordx4 v4, v[128:131], s[26:27] offset:1024 nt
	v_lshlrev_b32_e32 v28, 16, v48
	v_and_b32_e32 v29, 0xffff0000, v48
	v_lshlrev_b32_e32 v30, 16, v49
	v_and_b32_e32 v31, 0xffff0000, v49
	v_lshlrev_b32_e32 v32, 16, v50
	v_and_b32_e32 v33, 0xffff0000, v50
	v_lshlrev_b32_e32 v34, 16, v51
	v_and_b32_e32 v35, 0xffff0000, v51
	v_lshlrev_b32_e32 v36, 16, v52
	v_and_b32_e32 v37, 0xffff0000, v52
	v_lshlrev_b32_e32 v38, 16, v53
	v_and_b32_e32 v39, 0xffff0000, v53
	v_lshlrev_b32_e32 v44, 16, v54
	v_and_b32_e32 v45, 0xffff0000, v54
	v_lshlrev_b32_e32 v46, 16, v55
	v_and_b32_e32 v47, 0xffff0000, v55
	v_lshlrev_b32_e32 v56, 16, v56
	v_lshlrev_b32_e32 v57, 16, v57
	v_lshlrev_b32_e32 v58, 16, v58
	v_lshlrev_b32_e32 v59, 16, v59
	v_lshlrev_b32_e32 v60, 16, v60
	v_lshlrev_b32_e32 v61, 16, v61
	v_lshlrev_b32_e32 v62, 16, v62
	v_lshlrev_b32_e32 v63, 16, v63
	v_add_f32_e32 v108, v28, v29
	v_add_f32_e32 v108, v108, v30
	v_add_f32_e32 v108, v108, v31
	v_add_f32_e32 v108, v108, v32
	v_add_f32_e32 v108, v108, v33
	v_add_f32_e32 v108, v108, v34
	v_add_f32_e32 v108, v108, v35
	s_nop 1
	v_add_f32_dpp v109, v108, v108 quad_perm:[1,0,3,2] row_mask:0xf bank_mask:0xf
	s_nop 1
	v_add_f32_dpp v108, v109, v109 quad_perm:[2,3,0,1] row_mask:0xf bank_mask:0xf
	s_nop 1
	v_add_f32_dpp v109, v108, v108 row_half_mirror row_mask:0xf bank_mask:0xf
	v_mov_b32_e32 v108, v109
	v_mul_f32_e32 v108, 0x3c800000, v108
	v_pk_add_f32 v[28:29], v[28:29], v[108:109] op_sel_hi:[1,0] neg_lo:[0,1] neg_hi:[0,1]
	v_pk_add_f32 v[30:31], v[30:31], v[108:109] op_sel_hi:[1,0] neg_lo:[0,1] neg_hi:[0,1]
	v_pk_add_f32 v[32:33], v[32:33], v[108:109] op_sel_hi:[1,0] neg_lo:[0,1] neg_hi:[0,1]
	v_pk_add_f32 v[34:35], v[34:35], v[108:109] op_sel_hi:[1,0] neg_lo:[0,1] neg_hi:[0,1]
	v_pk_mul_f32 v[110:111], v[28:29], v[28:29]
	v_pk_mul_f32 v[112:113], v[30:31], v[30:31]
	v_pk_mul_f32 v[114:115], v[32:33], v[32:33]
	v_pk_mul_f32 v[116:117], v[34:35], v[34:35]
	v_add_f32_e32 v118, v110, v111
	v_add_f32_e32 v118, v112, v118
	v_add_f32_e32 v118, v113, v118
	v_add_f32_e32 v118, v114, v118
	v_add_f32_e32 v118, v115, v118
	v_add_f32_e32 v118, v116, v118
	v_add_f32_e32 v118, v117, v118
	s_nop 1
	v_add_f32_dpp v119, v118, v118 quad_perm:[1,0,3,2] row_mask:0xf bank_mask:0xf
	s_nop 1
	v_add_f32_dpp v118, v119, v119 quad_perm:[2,3,0,1] row_mask:0xf bank_mask:0xf
	s_nop 1
	v_add_f32_dpp v119, v118, v118 row_half_mirror row_mask:0xf bank_mask:0xf
	v_mov_b32_e32 v118, v119
	v_fmamk_f32 v118, v118, 0x3c800000, v100
	v_rsq_f32_e32 v118, v118
	v_mov_b32_e32 v120, v27
	v_pk_mul_f32 v[28:29], v[28:29], v[118:119] op_sel_hi:[1,0]
	v_pk_mul_f32 v[30:31], v[30:31], v[118:119] op_sel_hi:[1,0]
	v_pk_mul_f32 v[32:33], v[32:33], v[118:119] op_sel_hi:[1,0]
	v_pk_mul_f32 v[34:35], v[34:35], v[118:119] op_sel_hi:[1,0]
	v_pk_fma_f32 v[28:29], v[8:9], v[28:29], v[16:17]
	v_pk_fma_f32 v[30:31], v[10:11], v[30:31], v[18:19]
	v_pk_fma_f32 v[32:33], v[12:13], v[32:33], v[20:21]
	v_pk_fma_f32 v[34:35], v[14:15], v[34:35], v[22:23]
	v_pk_fma_f32 v[28:29], v[120:121], v[56:57], v[28:29] op_sel_hi:[0,1,1]
	v_pk_fma_f32 v[30:31], v[120:121], v[58:59], v[30:31] op_sel_hi:[0,1,1]
	v_pk_fma_f32 v[32:33], v[120:121], v[60:61], v[32:33] op_sel_hi:[0,1,1]
	v_pk_fma_f32 v[34:35], v[120:121], v[62:63], v[34:35] op_sel_hi:[0,1,1]
	v_pk_mul_f32 v[118:119], v[36:37], s[44:45]
	v_exp_f32_e32 v118, v118
	v_exp_f32_e32 v119, v119
	s_nop 0
	v_pk_add_f32 v[118:119], v[118:119], 1.0 op_sel_hi:[1,0]
	v_div_scale_f32 v122, s[72:73], v118, v118, v36
	v_rcp_f32_e32 v123, v122
	v_div_scale_f32 v124, vcc, v36, v118, v36
	v_fma_f32 v126, -v122, v123, 1.0
	v_fmac_f32_e32 v123, v126, v123
	v_mul_f32_e32 v125, v124, v123
	v_fma_f32 v126, -v122, v125, v124
	v_fmac_f32_e32 v125, v126, v123
	v_fma_f32 v122, -v122, v125, v124
	v_div_fmas_f32 v122, v122, v123, v125
	v_div_fixup_f32 v108, v122, v118, v36
	v_div_scale_f32 v122, s[72:73], v119, v119, v37
	v_rcp_f32_e32 v123, v122
	v_div_scale_f32 v124, vcc, v37, v119, v37
	v_fma_f32 v126, -v122, v123, 1.0
	v_fmac_f32_e32 v123, v126, v123
	v_mul_f32_e32 v125, v124, v123
	v_fma_f32 v126, -v122, v125, v124
	v_fmac_f32_e32 v125, v126, v123
	v_fma_f32 v122, -v122, v125, v124
	v_div_fmas_f32 v122, v122, v123, v125
	v_div_fixup_f32 v109, v122, v119, v37
	v_pk_mul_f32 v[28:29], v[108:109], v[28:29]
	v_cvt_pk_bf16_f32 v132, v28, v29
	v_pk_mul_f32 v[118:119], v[38:39], s[44:45]
	v_exp_f32_e32 v118, v118
	v_exp_f32_e32 v119, v119
	s_nop 0
	v_pk_add_f32 v[118:119], v[118:119], 1.0 op_sel_hi:[1,0]
	v_div_scale_f32 v122, s[72:73], v118, v118, v38
	v_rcp_f32_e32 v123, v122
	v_div_scale_f32 v124, vcc, v38, v118, v38
	v_fma_f32 v126, -v122, v123, 1.0
	v_fmac_f32_e32 v123, v126, v123
	v_mul_f32_e32 v125, v124, v123
	v_fma_f32 v126, -v122, v125, v124
	v_fmac_f32_e32 v125, v126, v123
	v_fma_f32 v122, -v122, v125, v124
	v_div_fmas_f32 v122, v122, v123, v125
	v_div_fixup_f32 v108, v122, v118, v38
	v_div_scale_f32 v122, s[72:73], v119, v119, v39
	v_rcp_f32_e32 v123, v122
	v_div_scale_f32 v124, vcc, v39, v119, v39
	v_fma_f32 v126, -v122, v123, 1.0
	v_fmac_f32_e32 v123, v126, v123
	v_mul_f32_e32 v125, v124, v123
	v_fma_f32 v126, -v122, v125, v124
	v_fmac_f32_e32 v125, v126, v123
	v_fma_f32 v122, -v122, v125, v124
	v_div_fmas_f32 v122, v122, v123, v125
	v_div_fixup_f32 v109, v122, v119, v39
	v_pk_mul_f32 v[30:31], v[108:109], v[30:31]
	v_cvt_pk_bf16_f32 v133, v30, v31
	v_pk_mul_f32 v[118:119], v[44:45], s[44:45]
	v_exp_f32_e32 v118, v118
	v_exp_f32_e32 v119, v119
	s_nop 0
	v_pk_add_f32 v[118:119], v[118:119], 1.0 op_sel_hi:[1,0]
	v_div_scale_f32 v122, s[72:73], v118, v118, v44
	v_rcp_f32_e32 v123, v122
	v_div_scale_f32 v124, vcc, v44, v118, v44
	v_fma_f32 v126, -v122, v123, 1.0
	v_fmac_f32_e32 v123, v126, v123
	v_mul_f32_e32 v125, v124, v123
	v_fma_f32 v126, -v122, v125, v124
	v_fmac_f32_e32 v125, v126, v123
	v_fma_f32 v122, -v122, v125, v124
	v_div_fmas_f32 v122, v122, v123, v125
	v_div_fixup_f32 v108, v122, v118, v44
	v_div_scale_f32 v122, s[72:73], v119, v119, v45
	v_rcp_f32_e32 v123, v122
	v_div_scale_f32 v124, vcc, v45, v119, v45
	v_fma_f32 v126, -v122, v123, 1.0
	v_fmac_f32_e32 v123, v126, v123
	v_mul_f32_e32 v125, v124, v123
	v_fma_f32 v126, -v122, v125, v124
	v_fmac_f32_e32 v125, v126, v123
	v_fma_f32 v122, -v122, v125, v124
	v_div_fmas_f32 v122, v122, v123, v125
	v_div_fixup_f32 v109, v122, v119, v45
	v_pk_mul_f32 v[32:33], v[108:109], v[32:33]
	v_cvt_pk_bf16_f32 v134, v32, v33
	v_pk_mul_f32 v[118:119], v[46:47], s[44:45]
	v_exp_f32_e32 v118, v118
	v_exp_f32_e32 v119, v119
	s_nop 0
	v_pk_add_f32 v[118:119], v[118:119], 1.0 op_sel_hi:[1,0]
	v_div_scale_f32 v122, s[72:73], v118, v118, v46
	v_rcp_f32_e32 v123, v122
	v_div_scale_f32 v124, vcc, v46, v118, v46
	v_fma_f32 v126, -v122, v123, 1.0
	v_fmac_f32_e32 v123, v126, v123
	v_mul_f32_e32 v125, v124, v123
	v_fma_f32 v126, -v122, v125, v124
	v_fmac_f32_e32 v125, v126, v123
	v_fma_f32 v122, -v122, v125, v124
	v_div_fmas_f32 v122, v122, v123, v125
	v_div_fixup_f32 v108, v122, v118, v46
	v_div_scale_f32 v122, s[72:73], v119, v119, v47
	v_rcp_f32_e32 v123, v122
	v_div_scale_f32 v124, vcc, v47, v119, v47
	v_fma_f32 v126, -v122, v123, 1.0
	v_fmac_f32_e32 v123, v126, v123
	v_mul_f32_e32 v125, v124, v123
	v_fma_f32 v126, -v122, v125, v124
	v_fmac_f32_e32 v125, v126, v123
	v_fma_f32 v122, -v122, v125, v124
	v_div_fmas_f32 v122, v122, v123, v125
	v_div_fixup_f32 v109, v122, v119, v47
	v_pk_mul_f32 v[34:35], v[108:109], v[34:35]
	v_cvt_pk_bf16_f32 v135, v34, v35
	global_store_dwordx4 v4, v[132:135], s[26:27] nt
	s_mov_b32 s50, 0
	s_add_i32 s12, s12, s22
	s_cmpk_lt_i32 s12, 0x100
	s_cbranch_scc0 .Lfm_nonext
	s_lshl_b32 s16, s12, 4
	s_add_i32 s16, s16, s91
	s_mul_i32 s17, s16, 0x2100
	s_add_u32 s24, s78, s17
	s_addc_u32 s25, s79, 0
	s_add_u32 s26, s24, 0x1900
	s_addc_u32 s27, s25, 0
	s_lshl_b32 s17, s16, 10
	s_add_u32 s28, s80, s17
	s_addc_u32 s29, s81, 0
	s_lshr_b32 s17, s16, 12
	s_lshl_b32 s17, s17, 11
	s_bfe_u32 s19, s16, 0x80004
	s_add_i32 s17, s17, s19
	s_mul_i32 s17, s17, 0x3180
	s_add_u32 s68, s86, s17
	s_addc_u32 s69, s87, 0
	s_and_b32 s19, s16, 15
	s_lshl_b32 s17, s19, 2
	s_addk_i32 s17, 0x3100
	s_add_u32 s30, s68, s17
	s_addc_u32 s31, s69, 0
	s_lshr_b32 s17, s19, 2
	s_lshl_b32 s17, s17, 7
	s_and_b32 s19, s19, 3
	s_lshl_b32 s19, s19, 1
	s_add_i32 s17, s17, s19
	s_addk_i32 s17, 0x2800
	s_add_u32 s70, s68, s17
	s_addc_u32 s71, s69, 0
	global_load_dword v24, v5, s[24:25] offset:3072
	global_load_dword v25, v5, s[24:25] offset:3104
	global_load_dword v26, v5, s[24:25] offset:3136
	global_load_dwordx4 v[28:31], v4, s[24:25] nt
	global_load_dwordx4 v[32:35], v4, s[24:25] offset:1024 nt
	global_load_dwordx4 v[36:39], v4, s[24:25] offset:2048 nt
	global_load_dwordx4 v[44:47], v4, s[26:27] offset:1024 nt
	global_load_dwordx4 v[48:51], v4, s[28:29] nt
	global_load_dwordx4 v[52:55], v4, s[26:27] nt
	global_load_dword v27, v6, s[30:31]
	global_load_ushort v56, v7, s[70:71] offset:0
	global_load_ushort v57, v7, s[70:71] offset:8
	global_load_ushort v58, v7, s[70:71] offset:16
	global_load_ushort v59, v7, s[70:71] offset:24
	global_load_ushort v60, v7, s[70:71] offset:32
	global_load_ushort v61, v7, s[70:71] offset:40
	global_load_ushort v62, v7, s[70:71] offset:48
	global_load_ushort v63, v7, s[70:71] offset:56
	s_waitcnt vmcnt(20)
	s_branch .Lfm_cb

.Lfm_cb:
	v_max3_f32 v127, v64, v65, v66
	v_sub_f32_e32 v102, v64, v127
	v_sub_f32_e32 v104, v65, v127
	v_sub_f32_e32 v106, v66, v127
	v_mul_f32_e32 v102, 0x3fb8aa3b, v102
	v_mul_f32_e32 v104, 0x3fb8aa3b, v104
	v_mul_f32_e32 v106, 0x3fb8aa3b, v106
	v_exp_f32_e32 v102, v102
	v_exp_f32_e32 v104, v104
	v_exp_f32_e32 v106, v106
	s_nop 0
	v_add_f32_e32 v127, v102, v104
	v_add_f32_e32 v127, v106, v127
	v_div_scale_f32 v122, s[72:73], v127, v127, 1.0
	v_rcp_f32_e32 v123, v122
	v_div_scale_f32 v124, vcc, 1.0, v127, 1.0
	v_fma_f32 v126, -v122, v123, 1.0
	v_fmac_f32_e32 v123, v126, v123
	v_mul_f32_e32 v125, v124, v123
	v_fma_f32 v126, -v122, v125, v124
	v_fmac_f32_e32 v125, v126, v123
	v_fma_f32 v122, -v122, v125, v124
	v_div_fmas_f32 v122, v122, v123, v125
	v_div_fixup_f32 v103, v122, v127, 1.0
	v_mul_f32_e32 v102, v102, v103
	v_mul_f32_e32 v104, v104, v103
	v_mul_f32_e32 v106, v106, v103
	v_lshlrev_b32_e32 v108, 16, v68
	v_and_b32_e32 v109, 0xffff0000, v68
	v_lshlrev_b32_e32 v110, 16, v72
	v_and_b32_e32 v111, 0xffff0000, v72
	v_lshlrev_b32_e32 v112, 16, v76
	v_and_b32_e32 v113, 0xffff0000, v76
	v_lshlrev_b32_e32 v114, 16, v80
	v_and_b32_e32 v115, 0xffff0000, v80
	v_pk_mul_f32 v[116:117], v[108:109], v[102:103] op_sel_hi:[1,0]
	v_pk_fma_f32 v[116:117], v[110:111], v[104:105], v[116:117] op_sel_hi:[1,0,1]
	v_pk_fma_f32 v[116:117], v[112:113], v[106:107], v[116:117] op_sel_hi:[1,0,1]
	v_pk_mul_f32 v[118:119], v[114:115], s[44:45]
	v_exp_f32_e32 v118, v118
	v_exp_f32_e32 v119, v119
	s_nop 0
	v_pk_add_f32 v[118:119], v[118:119], 1.0 op_sel_hi:[1,0]
	v_div_scale_f32 v122, s[72:73], v118, v118, v114
	v_rcp_f32_e32 v123, v122
	v_div_scale_f32 v124, vcc, v114, v118, v114
	v_fma_f32 v126, -v122, v123, 1.0
	v_fmac_f32_e32 v123, v126, v123
	v_mul_f32_e32 v125, v124, v123
	v_fma_f32 v126, -v122, v125, v124
	v_fmac_f32_e32 v125, v126, v123
	v_fma_f32 v122, -v122, v125, v124
	v_div_fmas_f32 v122, v122, v123, v125
	v_div_fixup_f32 v120, v122, v118, v114
	v_div_scale_f32 v122, s[72:73], v119, v119, v115
	v_rcp_f32_e32 v123, v122
	v_div_scale_f32 v124, vcc, v115, v119, v115
	v_fma_f32 v126, -v122, v123, 1.0
	v_fmac_f32_e32 v123, v126, v123
	v_mul_f32_e32 v125, v124, v123
	v_fma_f32 v126, -v122, v125, v124
	v_fmac_f32_e32 v125, v126, v123
	v_fma_f32 v122, -v122, v125, v124
	v_div_fmas_f32 v122, v122, v123, v125
	v_div_fixup_f32 v121, v122, v119, v115
	v_pk_mul_f32 v[116:117], v[120:121], v[116:117]
	v_cvt_pk_bf16_f32 v128, v116, v117
	v_lshlrev_b32_e32 v108, 16, v69
	v_and_b32_e32 v109, 0xffff0000, v69
	v_lshlrev_b32_e32 v110, 16, v73
	v_and_b32_e32 v111, 0xffff0000, v73
	v_lshlrev_b32_e32 v112, 16, v77
	v_and_b32_e32 v113, 0xffff0000, v77
	v_lshlrev_b32_e32 v114, 16, v81
	v_and_b32_e32 v115, 0xffff0000, v81
	v_pk_mul_f32 v[116:117], v[108:109], v[102:103] op_sel_hi:[1,0]
	v_pk_fma_f32 v[116:117], v[110:111], v[104:105], v[116:117] op_sel_hi:[1,0,1]
	v_pk_fma_f32 v[116:117], v[112:113], v[106:107], v[116:117] op_sel_hi:[1,0,1]
	v_pk_mul_f32 v[118:119], v[114:115], s[44:45]
	v_exp_f32_e32 v118, v118
	v_exp_f32_e32 v119, v119
	s_nop 0
	v_pk_add_f32 v[118:119], v[118:119], 1.0 op_sel_hi:[1,0]
	v_div_scale_f32 v122, s[72:73], v118, v118, v114
	v_rcp_f32_e32 v123, v122
	v_div_scale_f32 v124, vcc, v114, v118, v114
	v_fma_f32 v126, -v122, v123, 1.0
	v_fmac_f32_e32 v123, v126, v123
	v_mul_f32_e32 v125, v124, v123
	v_fma_f32 v126, -v122, v125, v124
	v_fmac_f32_e32 v125, v126, v123
	v_fma_f32 v122, -v122, v125, v124
	v_div_fmas_f32 v122, v122, v123, v125
	v_div_fixup_f32 v120, v122, v118, v114
	v_div_scale_f32 v122, s[72:73], v119, v119, v115
	v_rcp_f32_e32 v123, v122
	v_div_scale_f32 v124, vcc, v115, v119, v115
	v_fma_f32 v126, -v122, v123, 1.0
	v_fmac_f32_e32 v123, v126, v123
	v_mul_f32_e32 v125, v124, v123
	v_fma_f32 v126, -v122, v125, v124
	v_fmac_f32_e32 v125, v126, v123
	v_fma_f32 v122, -v122, v125, v124
	v_div_fmas_f32 v122, v122, v123, v125
	v_div_fixup_f32 v121, v122, v119, v115
	v_pk_mul_f32 v[116:117], v[120:121], v[116:117]
	v_cvt_pk_bf16_f32 v129, v116, v117
	v_lshlrev_b32_e32 v108, 16, v70
	v_and_b32_e32 v109, 0xffff0000, v70
	v_lshlrev_b32_e32 v110, 16, v74
	v_and_b32_e32 v111, 0xffff0000, v74
	v_lshlrev_b32_e32 v112, 16, v78
	v_and_b32_e32 v113, 0xffff0000, v78
	v_lshlrev_b32_e32 v114, 16, v82
	v_and_b32_e32 v115, 0xffff0000, v82
	v_pk_mul_f32 v[116:117], v[108:109], v[102:103] op_sel_hi:[1,0]
	v_pk_fma_f32 v[116:117], v[110:111], v[104:105], v[116:117] op_sel_hi:[1,0,1]
	v_pk_fma_f32 v[116:117], v[112:113], v[106:107], v[116:117] op_sel_hi:[1,0,1]
	v_pk_mul_f32 v[118:119], v[114:115], s[44:45]
	v_exp_f32_e32 v118, v118
	v_exp_f32_e32 v119, v119
	s_nop 0
	v_pk_add_f32 v[118:119], v[118:119], 1.0 op_sel_hi:[1,0]
	v_div_scale_f32 v122, s[72:73], v118, v118, v114
	v_rcp_f32_e32 v123, v122
	v_div_scale_f32 v124, vcc, v114, v118, v114
	v_fma_f32 v126, -v122, v123, 1.0
	v_fmac_f32_e32 v123, v126, v123
	v_mul_f32_e32 v125, v124, v123
	v_fma_f32 v126, -v122, v125, v124
	v_fmac_f32_e32 v125, v126, v123
	v_fma_f32 v122, -v122, v125, v124
	v_div_fmas_f32 v122, v122, v123, v125
	v_div_fixup_f32 v120, v122, v118, v114
	v_div_scale_f32 v122, s[72:73], v119, v119, v115
	v_rcp_f32_e32 v123, v122
	v_div_scale_f32 v124, vcc, v115, v119, v115
	v_fma_f32 v126, -v122, v123, 1.0
	v_fmac_f32_e32 v123, v126, v123
	v_mul_f32_e32 v125, v124, v123
	v_fma_f32 v126, -v122, v125, v124
	v_fmac_f32_e32 v125, v126, v123
	v_fma_f32 v122, -v122, v125, v124
	v_div_fmas_f32 v122, v122, v123, v125
	v_div_fixup_f32 v121, v122, v119, v115
	v_pk_mul_f32 v[116:117], v[120:121], v[116:117]
	v_cvt_pk_bf16_f32 v130, v116, v117
	v_lshlrev_b32_e32 v108, 16, v71
	v_and_b32_e32 v109, 0xffff0000, v71
	v_lshlrev_b32_e32 v110, 16, v75
	v_and_b32_e32 v111, 0xffff0000, v75
	v_lshlrev_b32_e32 v112, 16, v79
	v_and_b32_e32 v113, 0xffff0000, v79
	v_lshlrev_b32_e32 v114, 16, v83
	v_and_b32_e32 v115, 0xffff0000, v83
	v_pk_mul_f32 v[116:117], v[108:109], v[102:103] op_sel_hi:[1,0]
	v_pk_fma_f32 v[116:117], v[110:111], v[104:105], v[116:117] op_sel_hi:[1,0,1]
	v_pk_fma_f32 v[116:117], v[112:113], v[106:107], v[116:117] op_sel_hi:[1,0,1]
	v_pk_mul_f32 v[118:119], v[114:115], s[44:45]
	v_exp_f32_e32 v118, v118
	v_exp_f32_e32 v119, v119
	s_nop 0
	v_pk_add_f32 v[118:119], v[118:119], 1.0 op_sel_hi:[1,0]
	v_div_scale_f32 v122, s[72:73], v118, v118, v114
	v_rcp_f32_e32 v123, v122
	v_div_scale_f32 v124, vcc, v114, v118, v114
	v_fma_f32 v126, -v122, v123, 1.0
	v_fmac_f32_e32 v123, v126, v123
	v_mul_f32_e32 v125, v124, v123
	v_fma_f32 v126, -v122, v125, v124
	v_fmac_f32_e32 v125, v126, v123
	v_fma_f32 v122, -v122, v125, v124
	v_div_fmas_f32 v122, v122, v123, v125
	v_div_fixup_f32 v120, v122, v118, v114
	v_div_scale_f32 v122, s[72:73], v119, v119, v115
	v_rcp_f32_e32 v123, v122
	v_div_scale_f32 v124, vcc, v115, v119, v115
	v_fma_f32 v126, -v122, v123, 1.0
	v_fmac_f32_e32 v123, v126, v123
	v_mul_f32_e32 v125, v124, v123
	v_fma_f32 v126, -v122, v125, v124
	v_fmac_f32_e32 v125, v126, v123
	v_fma_f32 v122, -v122, v125, v124
	v_div_fmas_f32 v122, v122, v123, v125
	v_div_fixup_f32 v121, v122, v119, v115
	v_pk_mul_f32 v[116:117], v[120:121], v[116:117]
	v_cvt_pk_bf16_f32 v131, v116, v117
	global_store_dwordx4 v4, v[128:131], s[60:61] offset:1024 nt
	v_lshlrev_b32_e32 v68, 16, v84
	v_and_b32_e32 v69, 0xffff0000, v84
	v_lshlrev_b32_e32 v70, 16, v85
	v_and_b32_e32 v71, 0xffff0000, v85
	v_lshlrev_b32_e32 v72, 16, v86
	v_and_b32_e32 v73, 0xffff0000, v86
	v_lshlrev_b32_e32 v74, 16, v87
	v_and_b32_e32 v75, 0xffff0000, v87
	v_lshlrev_b32_e32 v76, 16, v88
	v_and_b32_e32 v77, 0xffff0000, v88
	v_lshlrev_b32_e32 v78, 16, v89
	v_and_b32_e32 v79, 0xffff0000, v89
	v_lshlrev_b32_e32 v80, 16, v90
	v_and_b32_e32 v81, 0xffff0000, v90
	v_lshlrev_b32_e32 v82, 16, v91
	v_and_b32_e32 v83, 0xffff0000, v91
	v_lshlrev_b32_e32 v92, 16, v92
	v_lshlrev_b32_e32 v93, 16, v93
	v_lshlrev_b32_e32 v94, 16, v94
	v_lshlrev_b32_e32 v95, 16, v95
	v_lshlrev_b32_e32 v96, 16, v96
	v_lshlrev_b32_e32 v97, 16, v97
	v_lshlrev_b32_e32 v98, 16, v98
	v_lshlrev_b32_e32 v99, 16, v99
	v_add_f32_e32 v108, v68, v69
	v_add_f32_e32 v108, v108, v70
	v_add_f32_e32 v108, v108, v71
	v_add_f32_e32 v108, v108, v72
	v_add_f32_e32 v108, v108, v73
	v_add_f32_e32 v108, v108, v74
	v_add_f32_e32 v108, v108, v75
	s_nop 1
	v_add_f32_dpp v109, v108, v108 quad_perm:[1,0,3,2] row_mask:0xf bank_mask:0xf
	s_nop 1
	v_add_f32_dpp v108, v109, v109 quad_perm:[2,3,0,1] row_mask:0xf bank_mask:0xf
	s_nop 1
	v_add_f32_dpp v109, v108, v108 row_half_mirror row_mask:0xf bank_mask:0xf
	v_mov_b32_e32 v108, v109
	v_mul_f32_e32 v108, 0x3c800000, v108
	v_pk_add_f32 v[68:69], v[68:69], v[108:109] op_sel_hi:[1,0] neg_lo:[0,1] neg_hi:[0,1]
	v_pk_add_f32 v[70:71], v[70:71], v[108:109] op_sel_hi:[1,0] neg_lo:[0,1] neg_hi:[0,1]
	v_pk_add_f32 v[72:73], v[72:73], v[108:109] op_sel_hi:[1,0] neg_lo:[0,1] neg_hi:[0,1]
	v_pk_add_f32 v[74:75], v[74:75], v[108:109] op_sel_hi:[1,0] neg_lo:[0,1] neg_hi:[0,1]
	v_pk_mul_f32 v[110:111], v[68:69], v[68:69]
	v_pk_mul_f32 v[112:113], v[70:71], v[70:71]
	v_pk_mul_f32 v[114:115], v[72:73], v[72:73]
	v_pk_mul_f32 v[116:117], v[74:75], v[74:75]
	v_add_f32_e32 v118, v110, v111
	v_add_f32_e32 v118, v112, v118
	v_add_f32_e32 v118, v113, v118
	v_add_f32_e32 v118, v114, v118
	v_add_f32_e32 v118, v115, v118
	v_add_f32_e32 v118, v116, v118
	v_add_f32_e32 v118, v117, v118
	s_nop 1
	v_add_f32_dpp v119, v118, v118 quad_perm:[1,0,3,2] row_mask:0xf bank_mask:0xf
	s_nop 1
	v_add_f32_dpp v118, v119, v119 quad_perm:[2,3,0,1] row_mask:0xf bank_mask:0xf
	s_nop 1
	v_add_f32_dpp v119, v118, v118 row_half_mirror row_mask:0xf bank_mask:0xf
	v_mov_b32_e32 v118, v119
	v_fmamk_f32 v118, v118, 0x3c800000, v100
	v_rsq_f32_e32 v118, v118
	v_mov_b32_e32 v120, v67
	v_pk_mul_f32 v[68:69], v[68:69], v[118:119] op_sel_hi:[1,0]
	v_pk_mul_f32 v[70:71], v[70:71], v[118:119] op_sel_hi:[1,0]
	v_pk_mul_f32 v[72:73], v[72:73], v[118:119] op_sel_hi:[1,0]
	v_pk_mul_f32 v[74:75], v[74:75], v[118:119] op_sel_hi:[1,0]
	v_pk_fma_f32 v[68:69], v[8:9], v[68:69], v[16:17]
	v_pk_fma_f32 v[70:71], v[10:11], v[70:71], v[18:19]
	v_pk_fma_f32 v[72:73], v[12:13], v[72:73], v[20:21]
	v_pk_fma_f32 v[74:75], v[14:15], v[74:75], v[22:23]
	v_pk_fma_f32 v[68:69], v[120:121], v[92:93], v[68:69] op_sel_hi:[0,1,1]
	v_pk_fma_f32 v[70:71], v[120:121], v[94:95], v[70:71] op_sel_hi:[0,1,1]
	v_pk_fma_f32 v[72:73], v[120:121], v[96:97], v[72:73] op_sel_hi:[0,1,1]
	v_pk_fma_f32 v[74:75], v[120:121], v[98:99], v[74:75] op_sel_hi:[0,1,1]
	v_pk_mul_f32 v[118:119], v[76:77], s[44:45]
	v_exp_f32_e32 v118, v118
	v_exp_f32_e32 v119, v119
	s_nop 0
	v_pk_add_f32 v[118:119], v[118:119], 1.0 op_sel_hi:[1,0]
	v_div_scale_f32 v122, s[72:73], v118, v118, v76
	v_rcp_f32_e32 v123, v122
	v_div_scale_f32 v124, vcc, v76, v118, v76
	v_fma_f32 v126, -v122, v123, 1.0
	v_fmac_f32_e32 v123, v126, v123
	v_mul_f32_e32 v125, v124, v123
	v_fma_f32 v126, -v122, v125, v124
	v_fmac_f32_e32 v125, v126, v123
	v_fma_f32 v122, -v122, v125, v124
	v_div_fmas_f32 v122, v122, v123, v125
	v_div_fixup_f32 v108, v122, v118, v76
	v_div_scale_f32 v122, s[72:73], v119, v119, v77
	v_rcp_f32_e32 v123, v122
	v_div_scale_f32 v124, vcc, v77, v119, v77
	v_fma_f32 v126, -v122, v123, 1.0
	v_fmac_f32_e32 v123, v126, v123
	v_mul_f32_e32 v125, v124, v123
	v_fma_f32 v126, -v122, v125, v124
	v_fmac_f32_e32 v125, v126, v123
	v_fma_f32 v122, -v122, v125, v124
	v_div_fmas_f32 v122, v122, v123, v125
	v_div_fixup_f32 v109, v122, v119, v77
	v_pk_mul_f32 v[68:69], v[108:109], v[68:69]
	v_cvt_pk_bf16_f32 v132, v68, v69
	v_pk_mul_f32 v[118:119], v[78:79], s[44:45]
	v_exp_f32_e32 v118, v118
	v_exp_f32_e32 v119, v119
	s_nop 0
	v_pk_add_f32 v[118:119], v[118:119], 1.0 op_sel_hi:[1,0]
	v_div_scale_f32 v122, s[72:73], v118, v118, v78
	v_rcp_f32_e32 v123, v122
	v_div_scale_f32 v124, vcc, v78, v118, v78
	v_fma_f32 v126, -v122, v123, 1.0
	v_fmac_f32_e32 v123, v126, v123
	v_mul_f32_e32 v125, v124, v123
	v_fma_f32 v126, -v122, v125, v124
	v_fmac_f32_e32 v125, v126, v123
	v_fma_f32 v122, -v122, v125, v124
	v_div_fmas_f32 v122, v122, v123, v125
	v_div_fixup_f32 v108, v122, v118, v78
	v_div_scale_f32 v122, s[72:73], v119, v119, v79
	v_rcp_f32_e32 v123, v122
	v_div_scale_f32 v124, vcc, v79, v119, v79
	v_fma_f32 v126, -v122, v123, 1.0
	v_fmac_f32_e32 v123, v126, v123
	v_mul_f32_e32 v125, v124, v123
	v_fma_f32 v126, -v122, v125, v124
	v_fmac_f32_e32 v125, v126, v123
	v_fma_f32 v122, -v122, v125, v124
	v_div_fmas_f32 v122, v122, v123, v125
	v_div_fixup_f32 v109, v122, v119, v79
	v_pk_mul_f32 v[70:71], v[108:109], v[70:71]
	v_cvt_pk_bf16_f32 v133, v70, v71
	v_pk_mul_f32 v[118:119], v[80:81], s[44:45]
	v_exp_f32_e32 v118, v118
	v_exp_f32_e32 v119, v119
	s_nop 0
	v_pk_add_f32 v[118:119], v[118:119], 1.0 op_sel_hi:[1,0]
	v_div_scale_f32 v122, s[72:73], v118, v118, v80
	v_rcp_f32_e32 v123, v122
	v_div_scale_f32 v124, vcc, v80, v118, v80
	v_fma_f32 v126, -v122, v123, 1.0
	v_fmac_f32_e32 v123, v126, v123
	v_mul_f32_e32 v125, v124, v123
	v_fma_f32 v126, -v122, v125, v124
	v_fmac_f32_e32 v125, v126, v123
	v_fma_f32 v122, -v122, v125, v124
	v_div_fmas_f32 v122, v122, v123, v125
	v_div_fixup_f32 v108, v122, v118, v80
	v_div_scale_f32 v122, s[72:73], v119, v119, v81
	v_rcp_f32_e32 v123, v122
	v_div_scale_f32 v124, vcc, v81, v119, v81
	v_fma_f32 v126, -v122, v123, 1.0
	v_fmac_f32_e32 v123, v126, v123
	v_mul_f32_e32 v125, v124, v123
	v_fma_f32 v126, -v122, v125, v124
	v_fmac_f32_e32 v125, v126, v123
	v_fma_f32 v122, -v122, v125, v124
	v_div_fmas_f32 v122, v122, v123, v125
	v_div_fixup_f32 v109, v122, v119, v81
	v_pk_mul_f32 v[72:73], v[108:109], v[72:73]
	v_cvt_pk_bf16_f32 v134, v72, v73
	v_pk_mul_f32 v[118:119], v[82:83], s[44:45]
	v_exp_f32_e32 v118, v118
	v_exp_f32_e32 v119, v119
	s_nop 0
	v_pk_add_f32 v[118:119], v[118:119], 1.0 op_sel_hi:[1,0]
	v_div_scale_f32 v122, s[72:73], v118, v118, v82
	v_rcp_f32_e32 v123, v122
	v_div_scale_f32 v124, vcc, v82, v118, v82
	v_fma_f32 v126, -v122, v123, 1.0
	v_fmac_f32_e32 v123, v126, v123
	v_mul_f32_e32 v125, v124, v123
	v_fma_f32 v126, -v122, v125, v124
	v_fmac_f32_e32 v125, v126, v123
	v_fma_f32 v122, -v122, v125, v124
	v_div_fmas_f32 v122, v122, v123, v125
	v_div_fixup_f32 v108, v122, v118, v82
	v_div_scale_f32 v122, s[72:73], v119, v119, v83
	v_rcp_f32_e32 v123, v122
	v_div_scale_f32 v124, vcc, v83, v119, v83
	v_fma_f32 v126, -v122, v123, 1.0
	v_fmac_f32_e32 v123, v126, v123
	v_mul_f32_e32 v125, v124, v123
	v_fma_f32 v126, -v122, v125, v124
	v_fmac_f32_e32 v125, v126, v123
	v_fma_f32 v122, -v122, v125, v124
	v_div_fmas_f32 v122, v122, v123, v125
	v_div_fixup_f32 v109, v122, v119, v83
	v_pk_mul_f32 v[74:75], v[108:109], v[74:75]
	v_cvt_pk_bf16_f32 v135, v74, v75
	global_store_dwordx4 v4, v[132:135], s[60:61] nt
	s_cmpk_lt_i32 s12, 0x100
	s_cbranch_scc1 .Lfm_loop
